# P11: next row's residual/routing loads issued before this row's LayerNorm (one more row in flight); chunk 0 of gamma/beta in registers
# baseline (speedup 1.0000x reference)
; DEVINL float bflo(unsigned u) { return __uint_as_float(u << 16); }
; DEVINL float bfhi(unsigned u) { return __uint_as_float(u & 0xffff0000u); }
; DEVINL void phase11(const Params& p) {
;     ...
;   for (int row = gw; row < T_; row += nw) {
;     const u16* hb = (const u16*)(p.ws + O_HBF) + (long)row * 2048;
;     float4 v[8];
;     float sum = 0.f;
; #pragma unroll
;     for (int i = 0; i < 8; ++i) {
;       const uint2 q = *(const uint2*)(hb + i * 256 + lane * 4);
;       v[i] = make_float4(ALPHA * bflo(q.x), ALPHA * bfhi(q.x), ALPHA * bflo(q.y), ALPHA * bfhi(q.y));
;     }
;     {
;       const int* inv = (const int*)(p.ws + O_INV) + row * 16;
;       const int myinv = inv[lane & 15];
; #pragma unroll 1
;       for (int e = 0; e < 16; ++e) {
;         const int er = __builtin_amdgcn_readlane(myinv, e);
;         if (er >= 0) {
;           const u16* eo = (const u16*)(p.ws + O_EO) + (long)er * 2048 + lane * 4;
; #pragma unroll
;           for (int i = 0; i < 8; ++i) {
;             uint2 q = *(const uint2*)(eo + i * 256);
;             v[i].x += bflo(q.x); v[i].y += bfhi(q.x); v[i].z += bflo(q.y); v[i].w += bfhi(q.y);
;           }
;         }
;       }
;     }
; #pragma unroll
;     for (int i = 0; i < 8; ++i) sum += v[i].x + v[i].y + v[i].z + v[i].w;
;     const float mu = allred64(sum) * (1.f / 2048.f);
.LBB0_1089:
	s_or_b64 exec, exec, s[0:1]
	s_waitcnt lgkmcnt(0)
	s_barrier
	s_movk_i32 s0, 0x2000
	v_ashrrev_i32_e32 v0, 6, v189
	v_add_u32_e32 v0, s52, v0
	v_cmp_gt_i32_e32 vcc, s0, v0
	s_and_saveexec_b64 s[0:1], vcc
	s_cbranch_execz .LBB0_1096
	v_lshlrev_b32_e32 v1, 2, v189
	v_and_b32_e32 v30, 0xfc, v1
	v_mov_b32_e32 v3, 0
	v_lshlrev_b32_e32 v2, 1, v30
	v_or_b32_e32 v32, 0x400, v30
	v_lshl_add_u64 v[4:5], s[92:93], 0, v[2:3]
	v_lshl_add_u64 v[8:9], s[8:9], 0, v[2:3]
	v_lshlrev_b32_e32 v2, 2, v30
	v_or_b32_e32 v34, 0x500, v30
	v_lshl_add_u64 v[10:11], s[86:87], 0, v[2:3]
	v_lshl_add_u64 v[12:13], s[88:89], 0, v[2:3]
	v_lshlrev_b32_e32 v2, 2, v32
	v_and_b32_e32 v1, 15, v189
	v_or_b32_e32 v36, 0x600, v30
	v_lshl_add_u64 v[14:15], s[86:87], 0, v[2:3]
	v_lshl_add_u64 v[16:17], s[88:89], 0, v[2:3]
	v_lshlrev_b32_e32 v2, 2, v34
	v_or_b32_e32 v38, 0x700, v30
	s_mov_b64 s[0:1], 0x17400000
	v_lshlrev_b32_e32 v6, 2, v1
	v_mov_b32_e32 v7, v3
	v_lshl_add_u64 v[18:19], s[86:87], 0, v[2:3]
	v_lshl_add_u64 v[20:21], s[88:89], 0, v[2:3]
	v_lshlrev_b32_e32 v2, 2, v36
	v_lshl_add_u64 v[4:5], v[4:5], 0, s[0:1]
	v_lshl_add_u64 v[6:7], s[92:93], 0, v[6:7]
	s_mov_b64 s[0:1], 0x21700000
	v_lshl_add_u64 v[22:23], s[86:87], 0, v[2:3]
	v_lshl_add_u64 v[24:25], s[88:89], 0, v[2:3]
	v_lshlrev_b32_e32 v2, 2, v38
	v_lshl_add_u64 v[6:7], v[6:7], 0, s[0:1]
	v_lshl_add_u64 v[26:27], s[86:87], 0, v[2:3]
	v_lshl_add_u64 v[28:29], s[88:89], 0, v[2:3]
	s_mov_b64 s[0:1], 0
	s_mov_b32 s2, 0x3f9837f0
	s_mov_b32 s5, 0
	v_lshlrev_b32_e32 v2, 2, v30
	v_lshlrev_b32_e32 v30, 2, v32
	v_lshlrev_b32_e32 v32, 2, v34
	v_lshlrev_b32_e32 v34, 2, v36
	v_mov_b32_e32 v72, 0x3727c5ac
	s_mov_b32 s3, 0x800000
	v_lshlrev_b32_e32 v36, 2, v38
	s_movk_i32 s6, 0x1fff
	v_mov_b32_e32 v73, 0x3a000000
	global_load_dwordx4 v[108:111], v[10:11], off offset:1024
	global_load_dwordx4 v[112:115], v[12:13], off offset:1024
	global_load_dwordx4 v[116:119], v[10:11], off offset:2048
	global_load_dwordx4 v[120:123], v[12:13], off offset:2048
	global_load_dwordx4 v[124:127], v[10:11], off offset:3072
	global_load_dwordx4 v[128:131], v[12:13], off offset:3072
	global_load_dwordx4 v[132:135], v[14:15], off
	global_load_dwordx4 v[136:139], v[16:17], off
	global_load_dwordx4 v[140:143], v[18:19], off
	global_load_dwordx4 v[144:147], v[20:21], off
	global_load_dwordx4 v[148:151], v[22:23], off
	global_load_dwordx4 v[152:155], v[24:25], off
	global_load_dwordx4 v[156:159], v[26:27], off
	global_load_dwordx4 v[160:163], v[28:29], off
	global_load_dwordx4 v[192:195], v[10:11], off
	global_load_dwordx4 v[196:199], v[12:13], off
	v_mov_b32_e32 v184, v0
	v_mov_b32_e32 v185, 0
	v_lshlrev_b64 v[182:183], 12, v[184:185]
	v_lshl_add_u64 v[182:183], v[4:5], 0, v[182:183]
	global_load_dwordx2 v[164:165], v[182:183], off
	global_load_dwordx2 v[166:167], v[182:183], off offset:512
	global_load_dwordx2 v[168:169], v[182:183], off offset:1024
	global_load_dwordx2 v[170:171], v[182:183], off offset:1536
	global_load_dwordx2 v[172:173], v[182:183], off offset:2048
	global_load_dwordx2 v[174:175], v[182:183], off offset:2560
	global_load_dwordx2 v[176:177], v[182:183], off offset:3072
	global_load_dwordx2 v[178:179], v[182:183], off offset:3584
	v_lshlrev_b32_e32 v186, 4, v0
	v_mov_b32_e32 v187, 0
	v_lshl_add_u64 v[186:187], v[186:187], 2, v[6:7]
	global_load_dword v180, v[186:187], off
	s_waitcnt vmcnt(0)
	s_branch .LBB0_1092
.LBB0_1091:
	v_add_f32_e32 v1, v71, v70
	v_add_f32_e32 v1, v68, v1
	v_add_f32_e32 v31, v67, v66
	v_add_f32_e32 v1, v69, v1
	v_add_f32_e32 v31, v64, v31
	v_add_f32_e32 v1, 0, v1
	v_add_f32_e32 v31, v65, v31
	v_add_f32_e32 v1, v31, v1
	v_add_f32_e32 v31, v63, v62
	v_add_f32_e32 v31, v60, v31
	v_add_f32_e32 v31, v61, v31
	v_add_f32_e32 v1, v31, v1
	v_add_f32_e32 v31, v59, v58
	v_add_f32_e32 v31, v56, v31
	v_pk_add_f32 v[74:75], v[54:55], v[50:51]
	v_add_f32_e32 v31, v57, v31
	v_pk_add_f32 v[74:75], v[48:49], v[74:75]
	v_add_f32_e32 v1, v31, v1
	v_pk_add_f32 v[74:75], v[52:53], v[74:75]
	v_mov_b32_e32 v31, 0
	v_add_f32_e32 v1, v75, v1
	v_add_f32_e32 v1, v74, v1
	v_pk_add_f32 v[74:75], v[46:47], v[42:43]
	v_mov_b32_e32 v100, v51
	v_pk_add_f32 v[74:75], v[40:41], v[74:75]
	v_mov_b32_e32 v101, v55
	v_pk_add_f32 v[74:75], v[44:45], v[74:75]
	v_mov_b32_e32 v51, v54
	v_add_f32_e32 v1, v75, v1
	v_add_f32_e32 v1, v74, v1
	s_nop 0
	s_nop 0
	v_add_f32_dpp v1, v1, v1 quad_perm:[1,0,3,2] row_mask:0xf bank_mask:0xf bound_ctrl:1
	v_mov_b32_e32 v102, v49
	v_mov_b32_e32 v103, v53
	v_add_f32_dpp v1, v1, v1 quad_perm:[2,3,0,1] row_mask:0xf bank_mask:0xf bound_ctrl:1
	v_mov_b32_e32 v49, v52
	v_mov_b32_e32 v33, v3
	v_add_f32_dpp v1, v1, v1 row_half_mirror row_mask:0xf bank_mask:0xf bound_ctrl:1
	v_mov_b32_e32 v35, v3
	v_add_u32_e32 v0, s60, v0
	v_mov_b32_e32 v184, v0
	v_mov_b32_e32 v185, 0
	v_lshlrev_b64 v[182:183], 12, v[184:185]
	v_lshl_add_u64 v[182:183], v[4:5], 0, v[182:183]
	global_load_dwordx2 v[164:165], v[182:183], off
	global_load_dwordx2 v[166:167], v[182:183], off offset:512
	global_load_dwordx2 v[168:169], v[182:183], off offset:1024
	global_load_dwordx2 v[170:171], v[182:183], off offset:1536
	global_load_dwordx2 v[172:173], v[182:183], off offset:2048
	global_load_dwordx2 v[174:175], v[182:183], off offset:2560
	global_load_dwordx2 v[176:177], v[182:183], off offset:3072
	global_load_dwordx2 v[178:179], v[182:183], off offset:3584
	v_lshlrev_b32_e32 v186, 4, v0
	v_mov_b32_e32 v187, 0
	v_lshl_add_u64 v[186:187], v[186:187], 2, v[6:7]
	global_load_dword v180, v[186:187], off
	v_add_f32_dpp v1, v1, v1 row_mirror row_mask:0xf bank_mask:0xf bound_ctrl:1
	v_mov_b32_e32 v37, v3
	s_nop 0
	v_mov_b32_dpp v31, v1 row_bcast:15 row_mask:0xa bank_mask:0xf
; DEVINL void phase11(const Params& p) {
;     ...
;     float sq = 0.f;
; #pragma unroll
;     for (int i = 0; i < 8; ++i) {
;       v[i].x -= mu; v[i].y -= mu; v[i].z -= mu; v[i].w -= mu;
;       sq += v[i].x * v[i].x + v[i].y * v[i].y + v[i].z * v[i].z + v[i].w * v[i].w;
;     }
;     const float rstd = rsqrtf(allred64(sq) * (1.f / 2048.f) + 1e-5f);
; #pragma unroll
;     for (int i = 0; i < 8; ++i) {
;       const int c = i * 256 + lane * 4;
;       float4 gq = *(const float4*)(p.ln2_g + c);
;       float4 bq = *(const float4*)(p.ln2_b + c);
;       const f32x4 ov = {v[i].x * rstd * gq.x + bq.x, v[i].y * rstd * gq.y + bq.y, v[i].z * rstd * gq.z + bq.z, v[i].w * rstd * gq.w + bq.w};
;       __builtin_nontemporal_store(ov, (f32x4*)(p.out + (long)row * 2048 + c));
;     }
	v_add_f32_e32 v1, v1, v31
	v_mov_b32_e32 v31, 0
	s_nop 1
	v_mov_b32_dpp v31, v1 row_bcast:31 row_mask:0xc bank_mask:0xf
	v_add_f32_e32 v1, v1, v31
	s_nop 0
	v_readlane_b32 s4, v1, 63
	s_nop 1
	v_mul_f32_e32 v82, s4, v73
	v_pk_add_f32 v[70:71], v[70:71], v[82:83] op_sel_hi:[1,0] neg_lo:[0,1] neg_hi:[0,1]
	v_pk_add_f32 v[66:67], v[66:67], v[82:83] op_sel_hi:[1,0] neg_lo:[0,1] neg_hi:[0,1]
	v_pk_mul_f32 v[84:85], v[70:71], v[70:71]
	v_pk_add_f32 v[68:69], v[68:69], v[82:83] op_sel_hi:[1,0] neg_lo:[0,1] neg_hi:[0,1]
	v_pk_mul_f32 v[88:89], v[66:67], v[66:67]
	v_pk_add_f32 v[64:65], v[64:65], v[82:83] op_sel_hi:[1,0] neg_lo:[0,1] neg_hi:[0,1]
	v_pk_mul_f32 v[86:87], v[68:69], v[68:69]
	v_pk_mul_f32 v[90:91], v[64:65], v[64:65]
	v_add_f32_e32 v1, v88, v89
	v_add_f32_e32 v31, v84, v85
	v_pk_add_f32 v[62:63], v[62:63], v[82:83] op_sel_hi:[1,0] neg_lo:[0,1] neg_hi:[0,1]
	v_pk_add_f32 v[100:101], v[100:101], v[82:83] op_sel_hi:[1,0] neg_lo:[0,1] neg_hi:[0,1]
	v_pk_add_f32 v[50:51], v[50:51], v[82:83] op_sel_hi:[1,0] neg_lo:[0,1] neg_hi:[0,1]
	v_add_f32_e32 v1, v90, v1
	v_add_f32_e32 v31, v86, v31
	v_pk_mul_f32 v[92:93], v[62:63], v[62:63]
	v_pk_add_f32 v[60:61], v[60:61], v[82:83] op_sel_hi:[1,0] neg_lo:[0,1] neg_hi:[0,1]
	v_mov_b32_e32 v54, v51
	v_mov_b32_e32 v55, v101
	v_add_f32_e32 v1, v91, v1
	v_add_f32_e32 v31, v87, v31
	v_pk_mul_f32 v[94:95], v[60:61], v[60:61]
	v_pk_add_f32 v[102:103], v[102:103], v[82:83] op_sel_hi:[1,0] neg_lo:[0,1] neg_hi:[0,1]
	v_pk_add_f32 v[48:49], v[48:49], v[82:83] op_sel_hi:[1,0] neg_lo:[0,1] neg_hi:[0,1]
	v_mov_b32_e32 v52, v50
	v_mov_b32_e32 v53, v100
	v_pk_mul_f32 v[54:55], v[54:55], v[54:55]
	v_add_f32_e32 v1, v31, v1
	v_add_f32_e32 v31, v92, v93
	v_pk_add_f32 v[58:59], v[58:59], v[82:83] op_sel_hi:[1,0] neg_lo:[0,1] neg_hi:[0,1]
	v_pk_fma_f32 v[52:53], v[52:53], v[52:53], v[54:55]
	v_mov_b32_e32 v54, v48
	v_mov_b32_e32 v55, v102
	v_add_f32_e32 v31, v94, v31
	v_pk_mul_f32 v[96:97], v[58:59], v[58:59]
	v_pk_add_f32 v[56:57], v[56:57], v[82:83] op_sel_hi:[1,0] neg_lo:[0,1] neg_hi:[0,1]
	v_pk_fma_f32 v[52:53], v[54:55], v[54:55], v[52:53]
	v_mov_b32_e32 v54, v43
	v_mov_b32_e32 v55, v47
	v_mov_b32_e32 v43, v46
	v_add_f32_e32 v31, v95, v31
	v_pk_mul_f32 v[98:99], v[56:57], v[56:57]
	v_mov_b32_e32 v104, v49
	v_mov_b32_e32 v105, v103
	v_pk_add_f32 v[54:55], v[54:55], v[82:83] op_sel_hi:[1,0] neg_lo:[0,1] neg_hi:[0,1]
	v_pk_add_f32 v[46:47], v[42:43], v[82:83] op_sel_hi:[1,0] neg_lo:[0,1] neg_hi:[0,1]
	v_add_f32_e32 v1, v31, v1
	v_add_f32_e32 v31, v96, v97
	v_pk_fma_f32 v[52:53], v[104:105], v[104:105], v[52:53]
	v_mov_b32_e32 v104, v41
	v_mov_b32_e32 v105, v45
	v_mov_b32_e32 v41, v44
	v_mov_b32_e32 v42, v47
	v_mov_b32_e32 v43, v55
	v_add_f32_e32 v31, v98, v31
	v_pk_add_f32 v[104:105], v[104:105], v[82:83] op_sel_hi:[1,0] neg_lo:[0,1] neg_hi:[0,1]
	v_pk_add_f32 v[82:83], v[40:41], v[82:83] op_sel_hi:[1,0] neg_lo:[0,1] neg_hi:[0,1]
	v_mov_b32_e32 v40, v46
	v_mov_b32_e32 v41, v54
	v_pk_mul_f32 v[42:43], v[42:43], v[42:43]
	v_add_f32_e32 v31, v99, v31
	v_pk_fma_f32 v[40:41], v[40:41], v[40:41], v[42:43]
	v_mov_b32_e32 v42, v82
	v_mov_b32_e32 v43, v104
	v_add_f32_e32 v1, v31, v1
	v_mov_b32_e32 v44, v83
	v_mov_b32_e32 v45, v105
	v_pk_fma_f32 v[40:41], v[42:43], v[42:43], v[40:41]
	v_add_f32_e32 v1, v53, v1
	v_pk_fma_f32 v[40:41], v[44:45], v[44:45], v[40:41]
	v_add_f32_e32 v1, v52, v1
	v_add_f32_e32 v1, v41, v1
	v_add_f32_e32 v1, v40, v1
	v_mov_b32_e32 v31, v3
	v_lshl_add_u64 v[52:53], v[38:39], 2, s[90:91]
	v_add_f32_dpp v1, v1, v1 quad_perm:[1,0,3,2] row_mask:0xf bank_mask:0xf bound_ctrl:1
	v_lshl_add_u64 v[84:85], v[52:53], 0, v[2:3]
	s_nop 0
	v_add_f32_dpp v1, v1, v1 quad_perm:[2,3,0,1] row_mask:0xf bank_mask:0xf bound_ctrl:1
	s_nop 1
	v_add_f32_dpp v1, v1, v1 row_half_mirror row_mask:0xf bank_mask:0xf bound_ctrl:1
	s_nop 1
	v_add_f32_dpp v1, v1, v1 row_mirror row_mask:0xf bank_mask:0xf bound_ctrl:1
	s_nop 1
	v_mov_b32_dpp v31, v1 row_bcast:15 row_mask:0xa bank_mask:0xf
	v_add_f32_e32 v1, v1, v31
	v_mov_b32_e32 v31, v3
	s_nop 1
	v_mov_b32_dpp v31, v1 row_bcast:31 row_mask:0xc bank_mask:0xf
	v_add_f32_e32 v1, v1, v31
	s_nop 0
	v_readlane_b32 s4, v1, 63
	s_nop 1
	v_fma_f32 v1, s4, v73, v72
	v_mul_f32_e32 v31, 0x4b800000, v1
	v_cmp_gt_f32_e32 vcc, s3, v1
	s_nop 1
	v_cndmask_b32_e32 v1, v1, v31, vcc
	v_rsq_f32_e32 v1, v1
	s_nop 0
	v_mul_f32_e32 v31, 0x45800000, v1
	v_cndmask_b32_e32 v86, v1, v31, vcc
	v_pk_mul_f32 v[38:39], v[70:71], v[86:87] op_sel_hi:[1,0]
	v_pk_mul_f32 v[40:41], v[68:69], v[86:87] op_sel_hi:[1,0]
	s_nop 0
	v_pk_fma_f32 v[38:39], v[192:193], v[38:39], v[196:197]
	v_pk_fma_f32 v[40:41], v[194:195], v[40:41], v[198:199]
	global_store_dwordx4 v[84:85], v[38:41], off nt
	v_pk_mul_f32 v[64:65], v[64:65], v[86:87] op_sel_hi:[1,0]
	v_pk_mul_f32 v[66:67], v[66:67], v[86:87] op_sel_hi:[1,0]
	v_pk_mul_f32 v[60:61], v[60:61], v[86:87] op_sel_hi:[1,0]
	v_pk_mul_f32 v[62:63], v[62:63], v[86:87] op_sel_hi:[1,0]
	v_pk_mul_f32 v[56:57], v[56:57], v[86:87] op_sel_hi:[1,0]
	v_pk_mul_f32 v[58:59], v[58:59], v[86:87] op_sel_hi:[1,0]
	v_mov_b32_e32 v31, v3
	v_pk_mul_f32 v[48:49], v[48:49], v[86:87] op_sel_hi:[1,0]
	v_pk_mul_f32 v[50:51], v[50:51], v[86:87] op_sel_hi:[1,0]
	v_pk_mul_f32 v[54:55], v[54:55], v[86:87] op_sel_hi:[1,0]
	v_cmp_lt_i32_e32 vcc, s6, v0
	v_pk_mul_f32 v[46:47], v[46:47], v[86:87] op_sel_hi:[1,0]
	s_or_b64 s[0:1], vcc, s[0:1]
	v_pk_fma_f32 v[42:43], v[66:67], v[108:109], v[112:113]
	v_pk_fma_f32 v[44:45], v[64:65], v[110:111], v[114:115]
	global_store_dwordx4 v[84:85], v[42:45], off offset:1024 nt
	v_pk_fma_f32 v[38:39], v[62:63], v[116:117], v[120:121]
	v_pk_fma_f32 v[40:41], v[60:61], v[118:119], v[122:123]
	global_store_dwordx4 v[84:85], v[38:41], off offset:2048 nt
	v_pk_mul_f32 v[60:61], v[100:101], v[86:87] op_sel_hi:[1,0]
	v_pk_fma_f32 v[42:43], v[58:59], v[124:125], v[128:129]
	v_pk_fma_f32 v[44:45], v[56:57], v[126:127], v[130:131]
	global_store_dwordx4 v[84:85], v[42:45], off offset:3072 nt
	v_pk_mul_f32 v[58:59], v[102:103], v[86:87] op_sel_hi:[1,0]
	v_lshl_add_u64 v[56:57], v[52:53], 0, v[30:31]
	v_pk_fma_f32 v[38:39], v[60:61], v[132:133], v[136:137]
	v_pk_fma_f32 v[40:41], v[58:59], v[134:135], v[138:139]
	global_store_dwordx4 v[56:57], v[38:41], off nt
	v_lshl_add_u64 v[56:57], v[52:53], 0, v[32:33]
	v_pk_fma_f32 v[42:43], v[50:51], v[140:141], v[144:145]
	v_pk_fma_f32 v[44:45], v[48:49], v[142:143], v[146:147]
	global_store_dwordx4 v[56:57], v[42:45], off nt
	v_pk_mul_f32 v[50:51], v[104:105], v[86:87] op_sel_hi:[1,0]
	v_lshl_add_u64 v[48:49], v[52:53], 0, v[34:35]
	v_pk_fma_f32 v[38:39], v[54:55], v[148:149], v[152:153]
	v_pk_fma_f32 v[40:41], v[50:51], v[150:151], v[154:155]
	global_store_dwordx4 v[48:49], v[38:41], off nt
	v_pk_mul_f32 v[50:51], v[82:83], v[86:87] op_sel_hi:[1,0]
	v_lshl_add_u64 v[48:49], v[52:53], 0, v[36:37]
	v_pk_fma_f32 v[42:43], v[46:47], v[156:157], v[160:161]
	v_pk_fma_f32 v[44:45], v[50:51], v[158:159], v[162:163]
	global_store_dwordx4 v[48:49], v[42:45], off nt
	s_andn2_b64 exec, exec, s[0:1]
	s_cbranch_execz .LBB0_1096
; DEVINL float bflo(unsigned u) { return __uint_as_float(u << 16); }
; DEVINL float bfhi(unsigned u) { return __uint_as_float(u & 0xffff0000u); }
; DEVINL void phase11(const Params& p) {
;     ...
;     const u16* hb = (const u16*)(p.ws + O_HBF) + (long)row * 2048;
;     float4 v[8];
;     float sum = 0.f;
; #pragma unroll
;     for (int i = 0; i < 8; ++i) {
;       const uint2 q = *(const uint2*)(hb + i * 256 + lane * 4);
;       v[i] = make_float4(ALPHA * bflo(q.x), ALPHA * bfhi(q.x), ALPHA * bflo(q.y), ALPHA * bfhi(q.y));
;     }
;     {
;       const int* inv = (const int*)(p.ws + O_INV) + row * 16;
;       const int myinv = inv[lane & 15];
.LBB0_1092:
	v_ashrrev_i32_e32 v1, 31, v0
	v_lshlrev_b64 v[38:39], 11, v[0:1]
	s_mov_b32 s7, s5
	s_waitcnt vmcnt(8)
	v_mov_b32_e32 v40, v164
	v_mov_b32_e32 v41, v165
	v_mov_b32_e32 v42, v166
	v_mov_b32_e32 v43, v167
	v_mov_b32_e32 v44, v168
	v_mov_b32_e32 v45, v169
	v_mov_b32_e32 v46, v170
	v_mov_b32_e32 v47, v171
	v_mov_b32_e32 v48, v172
	v_mov_b32_e32 v49, v173
	v_mov_b32_e32 v50, v174
	v_mov_b32_e32 v51, v175
	v_mov_b32_e32 v52, v176
	v_mov_b32_e32 v53, v177
	v_mov_b32_e32 v54, v178
	v_mov_b32_e32 v55, v179
	v_mov_b32_e32 v31, v180
	v_lshlrev_b32_e32 v56, 16, v40
	v_and_b32_e32 v57, 0xffff0000, v40
	v_lshlrev_b32_e32 v40, 16, v41
	v_and_b32_e32 v41, 0xffff0000, v41
	v_lshlrev_b32_e32 v58, 16, v42
	v_and_b32_e32 v59, 0xffff0000, v42
	v_lshlrev_b32_e32 v42, 16, v43
	v_and_b32_e32 v43, 0xffff0000, v43
	v_lshlrev_b32_e32 v60, 16, v44
	v_and_b32_e32 v61, 0xffff0000, v44
	v_lshlrev_b32_e32 v44, 16, v45
	v_and_b32_e32 v45, 0xffff0000, v45
	v_lshlrev_b32_e32 v74, 16, v46
	v_and_b32_e32 v75, 0xffff0000, v46
	v_lshlrev_b32_e32 v46, 16, v47
	v_and_b32_e32 v47, 0xffff0000, v47
	v_lshlrev_b32_e32 v77, 16, v48
	v_lshlrev_b32_e32 v76, 16, v50
	v_and_b32_e32 v79, 0xffff0000, v48
	v_and_b32_e32 v78, 0xffff0000, v50
	v_lshlrev_b32_e32 v81, 16, v49
	v_lshlrev_b32_e32 v80, 16, v51
	v_and_b32_e32 v83, 0xffff0000, v49
	v_and_b32_e32 v82, 0xffff0000, v51
	v_lshlrev_b32_e32 v85, 16, v52
	v_lshlrev_b32_e32 v84, 16, v54
	v_and_b32_e32 v87, 0xffff0000, v52
	v_and_b32_e32 v86, 0xffff0000, v54
	v_lshlrev_b32_e32 v89, 16, v53
	v_lshlrev_b32_e32 v88, 16, v55
	v_and_b32_e32 v91, 0xffff0000, v53
	v_and_b32_e32 v90, 0xffff0000, v55
	v_pk_mul_f32 v[70:71], v[56:57], s[2:3] op_sel_hi:[1,0]
	v_pk_mul_f32 v[68:69], v[40:41], s[2:3] op_sel_hi:[1,0]
	v_pk_mul_f32 v[66:67], v[58:59], s[2:3] op_sel_hi:[1,0]
	v_pk_mul_f32 v[64:65], v[42:43], s[2:3] op_sel_hi:[1,0]
	v_pk_mul_f32 v[62:63], v[60:61], s[2:3] op_sel_hi:[1,0]
	v_pk_mul_f32 v[60:61], v[44:45], s[2:3] op_sel_hi:[1,0]
	v_pk_mul_f32 v[58:59], v[74:75], s[2:3] op_sel_hi:[1,0]
	v_pk_mul_f32 v[56:57], v[46:47], s[2:3] op_sel_hi:[1,0]
	v_pk_mul_f32 v[50:51], v[76:77], s[2:3] op_sel_hi:[1,0]
	v_pk_mul_f32 v[54:55], v[78:79], s[2:3] op_sel_hi:[1,0]
	v_pk_mul_f32 v[48:49], v[80:81], s[2:3] op_sel_hi:[1,0]
	v_pk_mul_f32 v[52:53], v[82:83], s[2:3] op_sel_hi:[1,0]
	v_pk_mul_f32 v[42:43], v[84:85], s[2:3] op_sel_hi:[1,0]
	v_pk_mul_f32 v[46:47], v[86:87], s[2:3] op_sel_hi:[1,0]
	v_pk_mul_f32 v[40:41], v[88:89], s[2:3] op_sel_hi:[1,0]
	v_pk_mul_f32 v[44:45], v[90:91], s[2:3] op_sel_hi:[1,0]
	s_branch .LBB0_1094
